# hand-written adaLN-RMSNorm row loop: next-row prefetch + all 12 parameter loads issued up front
# speedup vs baseline: 1.3495x; 1.0036x over previous
.LBB0_134:
	s_waitcnt lgkmcnt(0)
	v_cndmask_b32_e64 v114, v4, v2, s[42:43]
	v_cndmask_b32_e64 v115, v5, v3, s[42:43]
	v_cndmask_b32_e64 v116, v6, v14, s[42:43]
	v_cndmask_b32_e64 v117, v7, v15, s[42:43]
	v_readfirstlane_b32 s100, v12
	v_readlane_b32 s101, v255, 4
	s_nop 3
	s_add_i32 s0, s100, 0xffffc000
	s_cmp_gt_i32 s100, 0x3fff
	s_cselect_b64 vcc, -1, 0
	s_cselect_b32 s0, s0, s100
	s_lshl_b32 s0, s0, 12
	s_mov_b32 s1, 0
	s_nop 1
	v_cndmask_b32_e32 v8, v114, v116, vcc
	v_cndmask_b32_e32 v9, v115, v117, vcc
	v_lshl_add_u64 v[8:9], v[8:9], 0, s[0:1]
	v_lshl_add_u64 v[8:9], v[8:9], 0, v[128:129]
	global_load_dwordx4 v[50:53], v[8:9], off nt
	global_load_dwordx4 v[54:57], v[8:9], off offset:1024 nt
	global_load_dwordx4 v[58:61], v[8:9], off offset:2048 nt
	global_load_dwordx4 v[62:65], v[8:9], off offset:3072 nt
	s_waitcnt vmcnt(0)
.Lnm_loop:
	s_waitcnt vmcnt(4)
	v_mov_b32_e32 v34, v50
	v_mov_b32_e32 v35, v51
	v_mov_b32_e32 v36, v52
	v_mov_b32_e32 v37, v53
	v_mov_b32_e32 v38, v54
	v_mov_b32_e32 v39, v55
	v_mov_b32_e32 v40, v56
	v_mov_b32_e32 v41, v57
	v_mov_b32_e32 v42, v58
	v_mov_b32_e32 v43, v59
	v_mov_b32_e32 v44, v60
	v_mov_b32_e32 v45, v61
	v_mov_b32_e32 v46, v62
	v_mov_b32_e32 v47, v63
	v_mov_b32_e32 v48, v64
	v_mov_b32_e32 v49, v65
	s_min_i32 s0, s100, 0x4000
	s_ashr_i32 s0, s0, 13
	s_add_i32 s0, s0, s78
	s_mul_i32 s0, s0, 0x3000
	s_mov_b32 s1, 0
	v_lshl_add_u64 v[10:11], v[16:17], 0, s[0:1]
	v_lshl_add_u64 v[10:11], v[10:11], 0, v[128:129]
	v_lshl_add_u64 v[118:119], v[10:11], 0, s[54:55]
	global_load_dwordx4 v[66:69], v[0:1], off
	global_load_dwordx4 v[70:73], v[0:1], off offset:1024
	global_load_dwordx4 v[74:77], v[0:1], off offset:2048
	global_load_dwordx4 v[78:81], v[0:1], off offset:3072
	global_load_dwordx4 v[82:85], v[118:119], off
	global_load_dwordx4 v[86:89], v[118:119], off offset:1024
	global_load_dwordx4 v[90:93], v[118:119], off offset:2048
	global_load_dwordx4 v[94:97], v[118:119], off offset:3072
	global_load_dwordx4 v[98:101], v[10:11], off
	global_load_dwordx4 v[102:105], v[10:11], off offset:1024
	global_load_dwordx4 v[106:109], v[10:11], off offset:2048
	global_load_dwordx4 v[110:113], v[10:11], off offset:3072
	s_add_i32 s6, s100, s101
	s_cmp_gt_i32 s6, 0x41ff
	s_cselect_b32 s7, s100, s6
	s_add_i32 s0, s7, 0xffffc000
	s_cmp_gt_i32 s7, 0x3fff
	s_cselect_b64 vcc, -1, 0
	s_cselect_b32 s0, s0, s7
	s_lshl_b32 s0, s0, 12
	s_mov_b32 s1, 0
	s_nop 1
	v_cndmask_b32_e32 v8, v114, v116, vcc
	v_cndmask_b32_e32 v9, v115, v117, vcc
	v_lshl_add_u64 v[8:9], v[8:9], 0, s[0:1]
	v_lshl_add_u64 v[8:9], v[8:9], 0, v[128:129]
	global_load_dwordx4 v[50:53], v[8:9], off nt
	global_load_dwordx4 v[54:57], v[8:9], off offset:1024 nt
	global_load_dwordx4 v[58:61], v[8:9], off offset:2048 nt
	global_load_dwordx4 v[62:65], v[8:9], off offset:3072 nt
	v_mul_f32_e32 v13, v34, v34
	v_fmac_f32_e32 v13, v35, v35
	v_fmac_f32_e32 v13, v36, v36
	v_fmac_f32_e32 v13, v37, v37
	v_fmac_f32_e32 v13, v38, v38
	v_fmac_f32_e32 v13, v39, v39
	v_fmac_f32_e32 v13, v40, v40
	v_fmac_f32_e32 v13, v41, v41
	v_fmac_f32_e32 v13, v42, v42
	v_fmac_f32_e32 v13, v43, v43
	v_fmac_f32_e32 v13, v44, v44
	v_fmac_f32_e32 v13, v45, v45
	v_fmac_f32_e32 v13, v46, v46
	v_fmac_f32_e32 v13, v47, v47
	v_fmac_f32_e32 v13, v48, v48
	v_fmac_f32_e32 v13, v49, v49
	ds_bpermute_b32 v21, v28, v13
	s_waitcnt lgkmcnt(0)
	v_add_f32_e32 v13, v13, v21
	ds_bpermute_b32 v21, v29, v13
	s_waitcnt lgkmcnt(0)
	v_add_f32_e32 v13, v13, v21
	ds_bpermute_b32 v21, v30, v13
	s_waitcnt lgkmcnt(0)
	v_add_f32_e32 v13, v13, v21
	ds_bpermute_b32 v21, v31, v13
	s_waitcnt lgkmcnt(0)
	v_add_f32_e32 v13, v13, v21
	ds_bpermute_b32 v21, v32, v13
	s_waitcnt lgkmcnt(0)
	v_add_f32_e32 v13, v13, v21
	ds_bpermute_b32 v21, v33, v13
	s_waitcnt lgkmcnt(0)
	v_add_f32_e32 v13, v13, v21
	v_fmamk_f32 v13, v13, 0x3a800000, v207
	v_mul_f32_e32 v21, 0x4b800000, v13
	v_cmp_gt_f32_e32 vcc, s82, v13
	s_nop 1
	v_cndmask_b32_e32 v13, v13, v21, vcc
	v_rsq_f32_e32 v13, v13
	s_nop 0
	v_mul_f32_e32 v21, 0x45800000, v13
	v_cndmask_b32_e32 v122, v13, v21, vcc
	s_lshl_b32 s0, s100, 11
	s_mov_b32 s1, 0
	v_lshl_add_u64 v[120:121], v[18:19], 0, s[0:1]
	s_waitcnt vmcnt(4)
	v_pk_mul_f32 v[34:35], v[34:35], v[122:123] op_sel_hi:[1,0]
	v_pk_mul_f32 v[36:37], v[36:37], v[122:123] op_sel_hi:[1,0]
	v_pk_mul_f32 v[34:35], v[66:67], v[34:35]
	v_pk_mul_f32 v[36:37], v[68:69], v[36:37]
	v_pk_add_f32 v[82:83], v[82:83], 1.0 op_sel_hi:[1,0]
	v_pk_add_f32 v[84:85], v[84:85], 1.0 op_sel_hi:[1,0]
	v_pk_fma_f32 v[34:35], v[82:83], v[34:35], v[98:99]
	v_pk_fma_f32 v[36:37], v[84:85], v[36:37], v[100:101]
	v_cvt_pk_bf16_f32 v34, v34, v35
	v_cvt_pk_bf16_f32 v35, v36, v37
	global_store_dwordx2 v[120:121], v[34:35], off
	v_pk_mul_f32 v[38:39], v[38:39], v[122:123] op_sel_hi:[1,0]
	v_pk_mul_f32 v[40:41], v[40:41], v[122:123] op_sel_hi:[1,0]
	v_pk_mul_f32 v[38:39], v[70:71], v[38:39]
	v_pk_mul_f32 v[40:41], v[72:73], v[40:41]
	v_pk_add_f32 v[86:87], v[86:87], 1.0 op_sel_hi:[1,0]
	v_pk_add_f32 v[88:89], v[88:89], 1.0 op_sel_hi:[1,0]
	v_pk_fma_f32 v[38:39], v[86:87], v[38:39], v[102:103]
	v_pk_fma_f32 v[40:41], v[88:89], v[40:41], v[104:105]
	v_cvt_pk_bf16_f32 v38, v38, v39
	v_cvt_pk_bf16_f32 v39, v40, v41
	global_store_dwordx2 v[120:121], v[38:39], off offset:512
	v_pk_mul_f32 v[42:43], v[42:43], v[122:123] op_sel_hi:[1,0]
	v_pk_mul_f32 v[44:45], v[44:45], v[122:123] op_sel_hi:[1,0]
	v_pk_mul_f32 v[42:43], v[74:75], v[42:43]
	v_pk_mul_f32 v[44:45], v[76:77], v[44:45]
	v_pk_add_f32 v[90:91], v[90:91], 1.0 op_sel_hi:[1,0]
	v_pk_add_f32 v[92:93], v[92:93], 1.0 op_sel_hi:[1,0]
	v_pk_fma_f32 v[42:43], v[90:91], v[42:43], v[106:107]
	v_pk_fma_f32 v[44:45], v[92:93], v[44:45], v[108:109]
	v_cvt_pk_bf16_f32 v42, v42, v43
	v_cvt_pk_bf16_f32 v43, v44, v45
	global_store_dwordx2 v[120:121], v[42:43], off offset:1024
	v_pk_mul_f32 v[46:47], v[46:47], v[122:123] op_sel_hi:[1,0]
	v_pk_mul_f32 v[48:49], v[48:49], v[122:123] op_sel_hi:[1,0]
	v_pk_mul_f32 v[46:47], v[78:79], v[46:47]
	v_pk_mul_f32 v[48:49], v[80:81], v[48:49]
	v_pk_add_f32 v[94:95], v[94:95], 1.0 op_sel_hi:[1,0]
	v_pk_add_f32 v[96:97], v[96:97], 1.0 op_sel_hi:[1,0]
	v_pk_fma_f32 v[46:47], v[94:95], v[46:47], v[110:111]
	v_pk_fma_f32 v[48:49], v[96:97], v[48:49], v[112:113]
	v_cvt_pk_bf16_f32 v46, v46, v47
	v_cvt_pk_bf16_f32 v47, v48, v49
	global_store_dwordx2 v[120:121], v[46:47], off offset:1536
	s_cmp_gt_i32 s6, 0x41ff
	s_mov_b32 s100, s6
	s_cbranch_scc0 .Lnm_loop

	.amdhsa_kernel _Z14fwd_megakernel6Params
		.amdhsa_group_segment_fixed_size 256
		.amdhsa_private_segment_fixed_size 0
		.amdhsa_kernarg_size 496
		.amdhsa_user_sgpr_count 2
		.amdhsa_user_sgpr_dispatch_ptr 0
		.amdhsa_user_sgpr_queue_ptr 0
		.amdhsa_user_sgpr_kernarg_segment_ptr 1
		.amdhsa_user_sgpr_dispatch_id 0
		.amdhsa_user_sgpr_kernarg_preload_length 0
		.amdhsa_user_sgpr_kernarg_preload_offset 0
		.amdhsa_user_sgpr_private_segment_size 0
		.amdhsa_uses_dynamic_stack 0
		.amdhsa_enable_private_segment 0
		.amdhsa_system_sgpr_workgroup_id_x 1
		.amdhsa_system_sgpr_workgroup_id_y 0
		.amdhsa_system_sgpr_workgroup_id_z 0
		.amdhsa_system_sgpr_workgroup_info 0
		.amdhsa_system_vgpr_workitem_id 2
		.amdhsa_next_free_vgpr 256
		.amdhsa_next_free_sgpr 102
		.amdhsa_accum_offset 256
		.amdhsa_reserve_vcc 1
		.amdhsa_float_round_mode_32 0
		.amdhsa_float_round_mode_16_64 0
		.amdhsa_float_denorm_mode_32 3
		.amdhsa_float_denorm_mode_16_64 3
		.amdhsa_dx10_clamp 1
		.amdhsa_ieee_mode 1
		.amdhsa_fp16_overflow 0
		.amdhsa_tg_split 0
		.amdhsa_exception_fp_ieee_invalid_op 0
		.amdhsa_exception_fp_denorm_src 0
		.amdhsa_exception_fp_ieee_div_zero 0
		.amdhsa_exception_fp_ieee_overflow 0
		.amdhsa_exception_fp_ieee_underflow 0
		.amdhsa_exception_fp_ieee_inexact 0
		.amdhsa_exception_int_div_zero 0
	.end_amdhsa_kernel

amdhsa.kernels:
  - .agpr_count:     0
    .args:
      - .offset:         0
        .size:           240
        .value_kind:     by_value
      - .offset:         240
        .size:           4
        .value_kind:     hidden_block_count_x
      - .offset:         244
        .size:           4
        .value_kind:     hidden_block_count_y
      - .offset:         248
        .size:           4
        .value_kind:     hidden_block_count_z
      - .offset:         252
        .size:           2
        .value_kind:     hidden_group_size_x
      - .offset:         254
        .size:           2
        .value_kind:     hidden_group_size_y
      - .offset:         256
        .size:           2
        .value_kind:     hidden_group_size_z
      - .offset:         258
        .size:           2
        .value_kind:     hidden_remainder_x
      - .offset:         260
        .size:           2
        .value_kind:     hidden_remainder_y
      - .offset:         262
        .size:           2
        .value_kind:     hidden_remainder_z
      - .offset:         280
        .size:           8
        .value_kind:     hidden_global_offset_x
      - .offset:         288
        .size:           8
        .value_kind:     hidden_global_offset_y
      - .offset:         296
        .size:           8
        .value_kind:     hidden_global_offset_z
      - .offset:         304
        .size:           2
        .value_kind:     hidden_grid_dims
      - .offset:         328
        .size:           8
        .value_kind:     hidden_multigrid_sync_arg
      - .offset:         360
        .size:           4
        .value_kind:     hidden_dynamic_lds_size
    .group_segment_fixed_size: 256
    .kernarg_segment_align: 8
    .kernarg_segment_size: 496
    .language:       OpenCL C
    .language_version:
      - 2
      - 0
    .max_flat_workgroup_size: 512
    .name:           _Z14fwd_megakernel6Params
    .private_segment_fixed_size: 0
    .sgpr_count:     108
    .sgpr_spill_count: 27
    .symbol:         _Z14fwd_megakernel6Params.kd
    .uniform_work_group_size: 1
    .uses_dynamic_stack: false
    .vgpr_count:     256
    .vgpr_spill_count: 0
    .wavefront_size: 64
